# attention importance-sum loop: the 8 LDS reads of an iteration issued together, j>0 guard by v_cndmask instead of four EXEC-masked branches
# baseline (speedup 1.0000x reference)
; DI void attn_item(const Params& P, int item, unsigned char* smem) {
;     ...
;     for (int e = 0; e < 4; ++e) { const int idx = tid + 512 * e, qq = idx >> 5, j = idx & 31, t = t0 + qq, cur = t >> 6;
;         float v = 0.f;
; #pragma unroll
;         for (int h = 0; h < 4; ++h) { v += impM[(h * 64 + qq) * 33 + j]; if (j > 0) v += impS[(h * 64 + qq) * 33 + j - 1]; }
;         const bool forced = (j == 0) || (j == cur) || (j == cur - 1);
;         impv[idx] = forced ? 1e6f : (j <= cur ? v : -1e9f); }
.LBB0_763:
	v_ashrrev_i32_e32 v72, 5, v71
	v_lshl_add_u32 v73, v72, 5, v72
	v_add_u32_e32 v216, v73, v84
	v_add_u32_e32 v217, v73, v2
	v_add_u32_e32 v218, v73, v68
	v_add_u32_e32 v219, v73, v69
	v_lshlrev_b32_e32 v216, 2, v216
	v_lshlrev_b32_e32 v217, 2, v217
	v_lshlrev_b32_e32 v218, 2, v218
	v_lshlrev_b32_e32 v219, 2, v219
	v_add_u32_e32 v216, 0x11000, v216
	v_add_u32_e32 v217, 0x11000, v217
	v_add_u32_e32 v218, 0x11000, v218
	v_add_u32_e32 v219, 0x11000, v219
	ds_read_b32 v208, v216
	ds_read_b32 v209, v216 offset:33788
	ds_read_b32 v210, v217
	ds_read_b32 v211, v217 offset:33788
	ds_read_b32 v212, v218
	ds_read_b32 v213, v218 offset:33788
	ds_read_b32 v214, v219
	ds_read_b32 v215, v219 offset:33788
	s_waitcnt lgkmcnt(7)
	v_add_f32_e32 v73, 0, v208
	s_waitcnt lgkmcnt(6)
	v_cndmask_b32_e64 v209, 0, v209, s[6:7]
	v_add_f32_e32 v73, v73, v209
	s_waitcnt lgkmcnt(5)
	v_add_f32_e32 v73, v73, v210
	s_waitcnt lgkmcnt(4)
	v_cndmask_b32_e64 v211, 0, v211, s[6:7]
	v_add_f32_e32 v73, v73, v211
	s_waitcnt lgkmcnt(3)
	v_add_f32_e32 v73, v73, v212
	s_waitcnt lgkmcnt(2)
	v_cndmask_b32_e64 v213, 0, v213, s[6:7]
	v_add_f32_e32 v73, v73, v213
	s_waitcnt lgkmcnt(1)
	v_add_f32_e32 v73, v73, v214
	s_waitcnt lgkmcnt(0)
	v_cndmask_b32_e64 v215, 0, v215, s[6:7]
	v_add_f32_e32 v73, v73, v215
	v_add_u32_e32 v72, v72, v1
	v_ashrrev_i32_e32 v72, 6, v72
	v_cmp_eq_u32_e64 s[0:1], v84, v72
	v_add_u32_e32 v74, -1, v72
	s_or_b64 s[4:5], vcc, s[0:1]
	v_cmp_eq_u32_e64 s[0:1], v84, v74
	v_cmp_le_i32_e64 s[8:9], v84, v72
	s_or_b64 s[0:1], s[4:5], s[0:1]
	v_add_u32_e32 v71, 0x200, v71
	v_cndmask_b32_e64 v72, v196, v73, s[8:9]
	v_add_u32_e32 v73, s2, v70
	s_addk_i32 s2, 0x800
	v_cndmask_b32_e64 v72, v72, v197, s[0:1]
	s_cmpk_eq_i32 s2, 0x2000
	ds_write_b32 v73, v72
	s_cbranch_scc0 .LBB0_763
